# vAA + nt on the f32 residual-stream loads in EpiResid (P4, P6) and the final RMSNorm
# baseline (speedup 1.0000x reference)
.LBB0_665:
	s_lshl_b32 s0, s73, 8
	s_add_i32 s0, s0, s67
	v_mbcnt_lo_u32_b32 v128, -1, 0
	v_mbcnt_hi_u32_b32 v128, -1, v128
	s_lshl_b32 s86, s72, 2
	v_and_or_b32 v156, v128, 15, s0
	s_lshl_b32 s0, s72, 8
	v_ashrrev_i32_e32 v129, 1, v128
	s_or_b32 s0, s0, s68
	v_and_b32_e32 v129, -8, v129
	v_add_u32_e32 v154, s0, v129
	v_ashrrev_i32_e32 v155, 31, v154
	v_ashrrev_i32_e32 v157, 31, v156
	v_cmp_gt_u32_e32 vcc, 16, v128
	v_lshl_add_u64 v[158:159], v[154:155], 2, s[46:47]
	v_lshlrev_b64 v[128:129], 12, v[156:157]
	v_lshl_add_u64 v[128:129], v[158:159], 0, v[128:129]
	global_load_dwordx4 v[164:167], v[128:129], off offset:16 nt
	global_load_dwordx4 v[168:171], v[128:129], off nt
	global_load_dwordx4 v[172:175], v[128:129], off offset:528 nt
	global_load_dwordx4 v[178:181], v[128:129], off offset:512 nt
	v_or_b32_e32 v160, 16, v156
	v_ashrrev_i32_e32 v161, 31, v160
	v_lshlrev_b64 v[128:129], 12, v[160:161]
	v_lshl_add_u64 v[132:133], v[158:159], 0, v[128:129]
	global_load_dwordx4 v[136:139], v[132:133], off offset:16 nt
	global_load_dwordx4 v[140:143], v[132:133], off nt
	global_load_dwordx4 v[128:131], v[132:133], off offset:528 nt
	s_nop 0
	global_load_dwordx4 v[132:135], v[132:133], off offset:512 nt
	v_lshlrev_b64 v[182:183], 10, v[156:157]
	v_lshl_add_u64 v[182:183], v[182:183], 0, v[154:155]
	s_ashr_i32 s87, s86, 31
	s_waitcnt vmcnt(0)
	v_pk_add_f32 v[122:123], v[122:123], v[166:167]
	v_pk_add_f32 v[126:127], v[126:127], v[170:171]
	v_pk_add_f32 v[124:125], v[124:125], v[168:169]
	v_lshl_add_u64 v[168:169], v[182:183], 2, s[36:37]
	v_pk_add_f32 v[120:121], v[120:121], v[164:165]
	global_store_dwordx4 v[168:169], v[124:127], off
	global_store_dwordx4 v[168:169], v[120:123], off offset:16
	v_cvt_pk_bf16_f32 v164, v124, v125
	v_cvt_pk_bf16_f32 v165, v126, v127
	v_cvt_pk_bf16_f32 v166, v120, v121
	v_lshl_add_u64 v[170:171], v[182:183], 1, s[48:49]
	v_mul_f32_e32 v125, v125, v125
	v_fmac_f32_e32 v125, v124, v124
	v_mul_f32_e32 v124, v127, v127
	v_fmac_f32_e32 v124, v126, v126
	v_mul_f32_e32 v121, v121, v121
	v_add_f32_e32 v124, v125, v124
	v_fmac_f32_e32 v121, v120, v120
	v_add_f32_e32 v120, v124, v121
	v_mul_f32_e32 v121, v123, v123
	v_fmac_f32_e32 v121, v122, v122
	v_pk_add_f32 v[118:119], v[118:119], v[180:181]
	v_pk_add_f32 v[116:117], v[116:117], v[178:179]
	v_cvt_pk_bf16_f32 v167, v122, v123
	global_store_dwordx4 v[170:171], v[164:167], off
	v_add_f32_e32 v124, v121, v120
	v_pk_add_f32 v[114:115], v[114:115], v[174:175]
	v_pk_add_f32 v[112:113], v[112:113], v[172:173]
	global_store_dwordx4 v[168:169], v[116:119], off offset:512
	global_store_dwordx4 v[168:169], v[112:115], off offset:528
	v_cvt_pk_bf16_f32 v120, v116, v117
	v_cvt_pk_bf16_f32 v121, v118, v119
	v_cvt_pk_bf16_f32 v122, v112, v113
	v_cvt_pk_bf16_f32 v123, v114, v115
	s_nop 0
	v_mul_f32_e32 v117, v117, v117
	v_fmac_f32_e32 v117, v116, v116
	v_mul_f32_e32 v116, v119, v119
	v_fmac_f32_e32 v116, v118, v118
	v_mul_f32_e32 v113, v113, v113
	v_add_f32_e32 v116, v117, v116
	v_fmac_f32_e32 v113, v112, v112
	v_add_f32_e32 v112, v116, v113
	v_mul_f32_e32 v113, v115, v115
	v_fmac_f32_e32 v113, v114, v114
	v_add_f32_e32 v112, v113, v112
	v_add_f32_e32 v112, v124, v112
	ds_swizzle_b32 v113, v112 offset:swizzle(SWAP,16)
	global_store_dwordx4 v[170:171], v[120:123], off offset:256
	s_waitcnt lgkmcnt(0)
	v_add_f32_e32 v112, v112, v113
	v_mov_b32_e32 v113, v112
	v_mov_b32_e32 v114, v112
	s_nop 1
	v_permlane32_swap_b32_e32 v113, v114
	s_and_saveexec_b64 s[0:1], vcc
	s_cbranch_execz .LBB0_667
	v_cmp_eq_u32_e64 s[44:45], v113, v112
	s_lshl_b32 s92, s66, 2
	s_nop 0
	v_cndmask_b32_e64 v113, v113, v114, s[44:45]
	v_add_f32_e32 v114, v112, v113
	v_lshlrev_b64 v[112:113], 6, v[156:157]
	v_lshl_add_u64 v[112:113], s[50:51], 0, v[112:113]
	v_lshl_add_u64 v[112:113], s[86:87], 2, v[112:113]
	v_lshl_add_u64 v[112:113], v[112:113], 0, s[92:93]
	global_store_dword v[112:113], v114, off

.LBB0_669:
	s_or_b64 exec, exec, s[0:1]
	v_or_b32_e32 v114, 32, v156
	v_ashrrev_i32_e32 v115, 31, v114
	v_lshlrev_b64 v[96:97], 12, v[114:115]
	v_lshl_add_u64 v[96:97], v[158:159], 0, v[96:97]
	global_load_dwordx4 v[116:119], v[96:97], off offset:16 nt
	global_load_dwordx4 v[120:123], v[96:97], off nt
	global_load_dwordx4 v[124:127], v[96:97], off offset:528 nt
	global_load_dwordx4 v[128:131], v[96:97], off offset:512 nt
	v_or_b32_e32 v112, 48, v156
	v_ashrrev_i32_e32 v113, 31, v112
	v_lshlrev_b64 v[96:97], 12, v[112:113]
	v_lshl_add_u64 v[100:101], v[158:159], 0, v[96:97]
	global_load_dwordx4 v[104:107], v[100:101], off offset:16 nt
	global_load_dwordx4 v[108:111], v[100:101], off nt
	global_load_dwordx4 v[96:99], v[100:101], off offset:528 nt
	s_nop 0
	global_load_dwordx4 v[100:103], v[100:101], off offset:512 nt
	v_lshlrev_b64 v[132:133], 10, v[114:115]
	v_lshl_add_u64 v[132:133], v[132:133], 0, v[154:155]
	s_waitcnt vmcnt(7)
	v_pk_add_f32 v[90:91], v[90:91], v[118:119]
	s_waitcnt vmcnt(6)
	v_pk_add_f32 v[94:95], v[94:95], v[122:123]
	v_pk_add_f32 v[92:93], v[92:93], v[120:121]
	v_lshl_add_u64 v[120:121], v[132:133], 2, s[36:37]
	v_pk_add_f32 v[88:89], v[88:89], v[116:117]
	global_store_dwordx4 v[120:121], v[92:95], off
	global_store_dwordx4 v[120:121], v[88:91], off offset:16
	v_cvt_pk_bf16_f32 v116, v92, v93
	v_cvt_pk_bf16_f32 v117, v94, v95
	v_cvt_pk_bf16_f32 v118, v88, v89
	v_lshl_add_u64 v[122:123], v[132:133], 1, s[48:49]
	v_mul_f32_e32 v93, v93, v93
	v_fmac_f32_e32 v93, v92, v92
	v_mul_f32_e32 v92, v95, v95
	v_fmac_f32_e32 v92, v94, v94
	v_mul_f32_e32 v89, v89, v89
	v_add_f32_e32 v92, v93, v92
	v_fmac_f32_e32 v89, v88, v88
	v_add_f32_e32 v88, v92, v89
	v_mul_f32_e32 v89, v91, v91
	v_fmac_f32_e32 v89, v90, v90
	s_waitcnt vmcnt(6)
	v_pk_add_f32 v[86:87], v[86:87], v[130:131]
	v_pk_add_f32 v[84:85], v[84:85], v[128:129]
	v_cvt_pk_bf16_f32 v119, v90, v91
	global_store_dwordx4 v[122:123], v[116:119], off
	v_add_f32_e32 v92, v89, v88
	v_pk_add_f32 v[82:83], v[82:83], v[126:127]
	v_pk_add_f32 v[80:81], v[80:81], v[124:125]
	global_store_dwordx4 v[120:121], v[84:87], off offset:512
	global_store_dwordx4 v[120:121], v[80:83], off offset:528
	v_cvt_pk_bf16_f32 v88, v84, v85
	v_cvt_pk_bf16_f32 v89, v86, v87
	v_cvt_pk_bf16_f32 v90, v80, v81
	v_cvt_pk_bf16_f32 v91, v82, v83
	s_nop 0
	v_mul_f32_e32 v85, v85, v85
	v_fmac_f32_e32 v85, v84, v84
	v_mul_f32_e32 v84, v87, v87
	v_fmac_f32_e32 v84, v86, v86
	v_mul_f32_e32 v81, v81, v81
	v_add_f32_e32 v84, v85, v84
	v_fmac_f32_e32 v81, v80, v80
	v_add_f32_e32 v80, v84, v81
	v_mul_f32_e32 v81, v83, v83
	v_fmac_f32_e32 v81, v82, v82
	v_add_f32_e32 v80, v81, v80
	v_add_f32_e32 v80, v92, v80
	ds_swizzle_b32 v81, v80 offset:swizzle(SWAP,16)
	global_store_dwordx4 v[122:123], v[88:91], off offset:256
	s_waitcnt lgkmcnt(0)
	v_add_f32_e32 v80, v80, v81
	v_mov_b32_e32 v81, v80
	v_mov_b32_e32 v82, v80
	s_nop 1
	v_permlane32_swap_b32_e32 v81, v82
	s_and_saveexec_b64 s[0:1], vcc
	s_cbranch_execz .LBB0_671
	v_cmp_eq_u32_e64 s[44:45], v81, v80
	s_lshl_b32 s92, s66, 2
	s_nop 0
	v_cndmask_b32_e64 v81, v81, v82, s[44:45]
	v_add_f32_e32 v82, v80, v81
	v_lshlrev_b64 v[80:81], 6, v[114:115]
	v_lshl_add_u64 v[80:81], s[50:51], 0, v[80:81]
	v_lshl_add_u64 v[80:81], s[86:87], 2, v[80:81]
	v_lshl_add_u64 v[80:81], v[80:81], 0, s[92:93]
	global_store_dword v[80:81], v82, off

.LBB0_673:
	s_or_b64 exec, exec, s[0:1]
	v_add_u32_e32 v82, 0x80, v156
	v_ashrrev_i32_e32 v83, 31, v82
	v_lshlrev_b64 v[64:65], 12, v[82:83]
	v_lshl_add_u64 v[64:65], v[158:159], 0, v[64:65]
	global_load_dwordx4 v[84:87], v[64:65], off offset:16 nt
	global_load_dwordx4 v[88:91], v[64:65], off nt
	global_load_dwordx4 v[92:95], v[64:65], off offset:528 nt
	global_load_dwordx4 v[96:99], v[64:65], off offset:512 nt
	v_add_u32_e32 v80, 0x90, v156
	v_ashrrev_i32_e32 v81, 31, v80
	v_lshlrev_b64 v[64:65], 12, v[80:81]
	v_lshl_add_u64 v[68:69], v[158:159], 0, v[64:65]
	global_load_dwordx4 v[72:75], v[68:69], off offset:16 nt
	global_load_dwordx4 v[76:79], v[68:69], off nt
	global_load_dwordx4 v[64:67], v[68:69], off offset:528 nt
	s_nop 0
	global_load_dwordx4 v[68:71], v[68:69], off offset:512 nt
	v_lshlrev_b64 v[100:101], 10, v[82:83]
	v_lshl_add_u64 v[100:101], v[100:101], 0, v[154:155]
	s_waitcnt vmcnt(7)
	v_pk_add_f32 v[58:59], v[58:59], v[86:87]
	s_waitcnt vmcnt(6)
	v_pk_add_f32 v[62:63], v[62:63], v[90:91]
	v_pk_add_f32 v[60:61], v[60:61], v[88:89]
	v_lshl_add_u64 v[88:89], v[100:101], 2, s[36:37]
	v_pk_add_f32 v[56:57], v[56:57], v[84:85]
	global_store_dwordx4 v[88:89], v[60:63], off
	global_store_dwordx4 v[88:89], v[56:59], off offset:16
	v_cvt_pk_bf16_f32 v84, v60, v61
	v_cvt_pk_bf16_f32 v85, v62, v63
	v_cvt_pk_bf16_f32 v86, v56, v57
	v_lshl_add_u64 v[90:91], v[100:101], 1, s[48:49]
	v_mul_f32_e32 v61, v61, v61
	v_fmac_f32_e32 v61, v60, v60
	v_mul_f32_e32 v60, v63, v63
	v_fmac_f32_e32 v60, v62, v62
	v_mul_f32_e32 v57, v57, v57
	v_add_f32_e32 v60, v61, v60
	v_fmac_f32_e32 v57, v56, v56
	v_add_f32_e32 v56, v60, v57
	v_mul_f32_e32 v57, v59, v59
	v_fmac_f32_e32 v57, v58, v58
	s_waitcnt vmcnt(6)
	v_pk_add_f32 v[54:55], v[54:55], v[98:99]
	v_pk_add_f32 v[52:53], v[52:53], v[96:97]
	v_cvt_pk_bf16_f32 v87, v58, v59
	global_store_dwordx4 v[90:91], v[84:87], off
	v_add_f32_e32 v60, v57, v56
	v_pk_add_f32 v[50:51], v[50:51], v[94:95]
	v_pk_add_f32 v[48:49], v[48:49], v[92:93]
	global_store_dwordx4 v[88:89], v[52:55], off offset:512
	global_store_dwordx4 v[88:89], v[48:51], off offset:528
	v_cvt_pk_bf16_f32 v56, v52, v53
	v_cvt_pk_bf16_f32 v57, v54, v55
	v_cvt_pk_bf16_f32 v58, v48, v49
	v_cvt_pk_bf16_f32 v59, v50, v51
	s_nop 0
	v_mul_f32_e32 v53, v53, v53
	v_fmac_f32_e32 v53, v52, v52
	v_mul_f32_e32 v52, v55, v55
	v_fmac_f32_e32 v52, v54, v54
	v_mul_f32_e32 v49, v49, v49
	v_add_f32_e32 v52, v53, v52
	v_fmac_f32_e32 v49, v48, v48
	v_add_f32_e32 v48, v52, v49
	v_mul_f32_e32 v49, v51, v51
	v_fmac_f32_e32 v49, v50, v50
	v_add_f32_e32 v48, v49, v48
	v_add_f32_e32 v48, v60, v48
	ds_swizzle_b32 v49, v48 offset:swizzle(SWAP,16)
	global_store_dwordx4 v[90:91], v[56:59], off offset:256
	s_waitcnt lgkmcnt(0)
	v_add_f32_e32 v48, v48, v49
	v_mov_b32_e32 v49, v48
	v_mov_b32_e32 v50, v48
	s_nop 1
	v_permlane32_swap_b32_e32 v49, v50
	s_and_saveexec_b64 s[0:1], vcc
	s_cbranch_execz .LBB0_675
	v_cmp_eq_u32_e64 s[44:45], v49, v48
	s_lshl_b32 s92, s66, 2
	s_nop 0
	v_cndmask_b32_e64 v49, v49, v50, s[44:45]
	v_add_f32_e32 v50, v48, v49
	v_lshlrev_b64 v[48:49], 6, v[82:83]
	v_lshl_add_u64 v[48:49], s[50:51], 0, v[48:49]
	v_lshl_add_u64 v[48:49], s[86:87], 2, v[48:49]
	v_lshl_add_u64 v[48:49], v[48:49], 0, s[92:93]
	global_store_dword v[48:49], v50, off

.LBB0_677:
	s_or_b64 exec, exec, s[0:1]
	v_add_u32_e32 v50, 0xa0, v156
	v_ashrrev_i32_e32 v51, 31, v50
	v_lshlrev_b64 v[32:33], 12, v[50:51]
	v_lshl_add_u64 v[32:33], v[158:159], 0, v[32:33]
	global_load_dwordx4 v[52:55], v[32:33], off offset:16 nt
	global_load_dwordx4 v[56:59], v[32:33], off nt
	global_load_dwordx4 v[60:63], v[32:33], off offset:528 nt
	global_load_dwordx4 v[64:67], v[32:33], off offset:512 nt
	v_add_u32_e32 v48, 0xb0, v156
	v_ashrrev_i32_e32 v49, 31, v48
	v_lshlrev_b64 v[32:33], 12, v[48:49]
	v_lshl_add_u64 v[36:37], v[158:159], 0, v[32:33]
	global_load_dwordx4 v[40:43], v[36:37], off offset:16 nt
	global_load_dwordx4 v[44:47], v[36:37], off nt
	global_load_dwordx4 v[32:35], v[36:37], off offset:528 nt
	s_nop 0
	global_load_dwordx4 v[36:39], v[36:37], off offset:512 nt
	v_lshlrev_b64 v[68:69], 10, v[50:51]
	v_lshl_add_u64 v[68:69], v[68:69], 0, v[154:155]
	s_waitcnt vmcnt(7)
	v_pk_add_f32 v[26:27], v[26:27], v[54:55]
	s_waitcnt vmcnt(6)
	v_pk_add_f32 v[30:31], v[30:31], v[58:59]
	v_pk_add_f32 v[28:29], v[28:29], v[56:57]
	v_lshl_add_u64 v[56:57], v[68:69], 2, s[36:37]
	v_pk_add_f32 v[24:25], v[24:25], v[52:53]
	global_store_dwordx4 v[56:57], v[28:31], off
	global_store_dwordx4 v[56:57], v[24:27], off offset:16
	v_cvt_pk_bf16_f32 v52, v28, v29
	v_cvt_pk_bf16_f32 v53, v30, v31
	v_cvt_pk_bf16_f32 v54, v24, v25
	v_lshl_add_u64 v[58:59], v[68:69], 1, s[48:49]
	v_mul_f32_e32 v29, v29, v29
	v_fmac_f32_e32 v29, v28, v28
	v_mul_f32_e32 v28, v31, v31
	v_fmac_f32_e32 v28, v30, v30
	v_mul_f32_e32 v25, v25, v25
	v_add_f32_e32 v28, v29, v28
	v_fmac_f32_e32 v25, v24, v24
	v_add_f32_e32 v24, v28, v25
	v_mul_f32_e32 v25, v27, v27
	v_fmac_f32_e32 v25, v26, v26
	s_waitcnt vmcnt(6)
	v_pk_add_f32 v[22:23], v[22:23], v[66:67]
	v_pk_add_f32 v[20:21], v[20:21], v[64:65]
	v_cvt_pk_bf16_f32 v55, v26, v27
	global_store_dwordx4 v[58:59], v[52:55], off
	v_add_f32_e32 v28, v25, v24
	v_pk_add_f32 v[18:19], v[18:19], v[62:63]
	v_pk_add_f32 v[16:17], v[16:17], v[60:61]
	global_store_dwordx4 v[56:57], v[20:23], off offset:512
	global_store_dwordx4 v[56:57], v[16:19], off offset:528
	v_cvt_pk_bf16_f32 v24, v20, v21
	v_cvt_pk_bf16_f32 v25, v22, v23
	v_cvt_pk_bf16_f32 v26, v16, v17
	v_cvt_pk_bf16_f32 v27, v18, v19
	s_nop 0
	v_mul_f32_e32 v21, v21, v21
	v_fmac_f32_e32 v21, v20, v20
	v_mul_f32_e32 v20, v23, v23
	v_fmac_f32_e32 v20, v22, v22
	v_mul_f32_e32 v17, v17, v17
	v_add_f32_e32 v20, v21, v20
	v_fmac_f32_e32 v17, v16, v16
	v_add_f32_e32 v16, v20, v17
	v_mul_f32_e32 v17, v19, v19
	v_fmac_f32_e32 v17, v18, v18
	v_add_f32_e32 v16, v17, v16
	v_add_f32_e32 v16, v28, v16
	ds_swizzle_b32 v17, v16 offset:swizzle(SWAP,16)
	global_store_dwordx4 v[58:59], v[24:27], off offset:256
	s_waitcnt lgkmcnt(0)
	v_add_f32_e32 v16, v16, v17
	v_mov_b32_e32 v17, v16
	v_mov_b32_e32 v18, v16
	s_nop 1
	v_permlane32_swap_b32_e32 v17, v18
	s_and_saveexec_b64 s[0:1], vcc
	s_cbranch_execz .LBB0_679
	v_cmp_eq_u32_e64 s[44:45], v17, v16
	s_lshl_b32 s92, s66, 2
	s_nop 0
	v_cndmask_b32_e64 v17, v17, v18, s[44:45]
	v_add_f32_e32 v18, v16, v17
	v_lshlrev_b64 v[16:17], 6, v[50:51]
	v_lshl_add_u64 v[16:17], s[50:51], 0, v[16:17]
	v_lshl_add_u64 v[16:17], s[86:87], 2, v[16:17]
	v_lshl_add_u64 v[16:17], v[16:17], 0, s[92:93]
	global_store_dword v[16:17], v18, off

.LBB0_933:
	s_lshl_b32 s0, s68, 8
	s_add_i32 s0, s0, s60
	v_mbcnt_lo_u32_b32 v182, -1, 0
	v_mbcnt_hi_u32_b32 v182, -1, v182
	s_lshl_b32 s54, s67, 2
	v_and_or_b32 v156, v182, 15, s0
	s_lshl_b32 s0, s67, 8
	v_ashrrev_i32_e32 v128, 1, v182
	s_or_b32 s0, s0, s61
	v_and_b32_e32 v128, -8, v128
	v_add_u32_e32 v154, s0, v128
	v_ashrrev_i32_e32 v155, 31, v154
	v_ashrrev_i32_e32 v157, 31, v156
	v_lshl_add_u64 v[158:159], v[154:155], 2, s[30:31]
	v_lshlrev_b64 v[128:129], 12, v[156:157]
	v_lshl_add_u64 v[174:175], v[158:159], 0, v[128:129]
	global_load_dwordx4 v[166:169], v[174:175], off nt
	global_load_dwordx4 v[170:173], v[174:175], off offset:16 nt
	global_load_dwordx4 v[178:181], v[174:175], off offset:512 nt
	global_load_dwordx4 v[186:189], v[174:175], off offset:528 nt
	v_or_b32_e32 v160, 16, v156
	v_ashrrev_i32_e32 v161, 31, v160
	v_lshlrev_b64 v[128:129], 12, v[160:161]
	v_lshl_add_u64 v[162:163], v[158:159], 0, v[128:129]
	global_load_dwordx4 v[136:139], v[162:163], off offset:16 nt
	global_load_dwordx4 v[140:143], v[162:163], off nt
	global_load_dwordx4 v[128:131], v[162:163], off offset:528 nt
	global_load_dwordx4 v[132:135], v[162:163], off offset:512 nt
	v_cmp_gt_u32_e32 vcc, 16, v182
	v_lshlrev_b64 v[182:183], 10, v[156:157]
	v_lshl_add_u64 v[182:183], v[182:183], 0, v[154:155]
	v_lshl_add_u64 v[182:183], v[182:183], 1, s[38:39]
	s_ashr_i32 s55, s54, 31
	s_waitcnt vmcnt(0)
	v_pk_add_f32 v[126:127], v[126:127], v[168:169]
	v_pk_add_f32 v[124:125], v[124:125], v[166:167]
	v_pk_add_f32 v[118:119], v[118:119], v[180:181]
	v_pk_add_f32 v[116:117], v[116:117], v[178:179]
	v_pk_add_f32 v[122:123], v[122:123], v[172:173]
	v_pk_add_f32 v[120:121], v[120:121], v[170:171]
	v_pk_add_f32 v[112:113], v[112:113], v[186:187]
	global_store_dwordx4 v[174:175], v[124:127], off
	global_store_dwordx4 v[174:175], v[120:123], off offset:16
	v_cvt_pk_bf16_f32 v166, v124, v125
	v_cvt_pk_bf16_f32 v167, v126, v127
	v_mul_f32_e32 v170, v117, v117
	v_mul_f32_e32 v125, v125, v125
	v_mul_f32_e32 v127, v127, v127
	v_mul_f32_e32 v171, v119, v119
	v_pk_add_f32 v[114:115], v[114:115], v[188:189]
	v_cvt_pk_bf16_f32 v168, v120, v121
	v_mul_f32_e32 v121, v121, v121
	v_mul_f32_e32 v172, v113, v113
	v_fmac_f32_e32 v125, v124, v124
	v_fmac_f32_e32 v127, v126, v126
	v_fmac_f32_e32 v170, v116, v116
	v_fmac_f32_e32 v171, v118, v118
	v_cvt_pk_bf16_f32 v169, v122, v123
	v_mul_f32_e32 v123, v123, v123
	v_mul_f32_e32 v173, v115, v115
	global_store_dwordx4 v[182:183], v[166:169], off
	v_fmac_f32_e32 v121, v120, v120
	global_store_dwordx4 v[174:175], v[116:119], off offset:512
	global_store_dwordx4 v[174:175], v[112:115], off offset:528
	v_cvt_pk_bf16_f32 v120, v116, v117
	v_fmac_f32_e32 v172, v112, v112
	v_add_f32_e32 v116, v125, v127
	v_add_f32_e32 v117, v170, v171
	v_fmac_f32_e32 v123, v122, v122
	v_fmac_f32_e32 v173, v114, v114
	v_add_f32_e32 v116, v116, v121
	v_add_f32_e32 v117, v117, v172
	v_add_f32_e32 v116, v123, v116
	v_add_f32_e32 v117, v173, v117
	v_add_f32_e32 v116, v116, v117
	ds_swizzle_b32 v117, v116 offset:swizzle(SWAP,16)
	v_cvt_pk_bf16_f32 v121, v118, v119
	v_cvt_pk_bf16_f32 v122, v112, v113
	v_cvt_pk_bf16_f32 v123, v114, v115
	global_store_dwordx4 v[182:183], v[120:123], off offset:256
	s_waitcnt lgkmcnt(0)
	v_add_f32_e32 v112, v116, v117
	v_mov_b32_e32 v113, v112
	v_mov_b32_e32 v114, v112
	s_nop 1
	v_permlane32_swap_b32_e32 v113, v114
	s_and_saveexec_b64 s[0:1], vcc
	s_cbranch_execz .LBB0_935
	v_cmp_eq_u32_e64 s[42:43], v113, v112
	s_lshl_b32 s92, s57, 2
	s_nop 0
	v_cndmask_b32_e64 v113, v113, v114, s[42:43]
	v_add_f32_e32 v114, v112, v113
	v_lshlrev_b64 v[112:113], 6, v[156:157]
	v_lshl_add_u64 v[112:113], s[44:45], 0, v[112:113]
	v_lshl_add_u64 v[112:113], s[54:55], 2, v[112:113]
	v_lshl_add_u64 v[112:113], v[112:113], 0, s[92:93]
	global_store_dword v[112:113], v114, off

.LBB0_937:
	s_or_b64 exec, exec, s[0:1]
	v_or_b32_e32 v116, 32, v156
	v_ashrrev_i32_e32 v117, 31, v116
	v_lshlrev_b64 v[96:97], 12, v[116:117]
	v_lshl_add_u64 v[134:135], v[158:159], 0, v[96:97]
	global_load_dwordx4 v[118:121], v[134:135], off nt
	global_load_dwordx4 v[122:125], v[134:135], off offset:16 nt
	global_load_dwordx4 v[126:129], v[134:135], off offset:512 nt
	global_load_dwordx4 v[130:133], v[134:135], off offset:528 nt
	v_or_b32_e32 v112, 48, v156
	v_ashrrev_i32_e32 v113, 31, v112
	v_lshlrev_b64 v[96:97], 12, v[112:113]
	v_lshl_add_u64 v[114:115], v[158:159], 0, v[96:97]
	global_load_dwordx4 v[104:107], v[114:115], off offset:16 nt
	global_load_dwordx4 v[108:111], v[114:115], off nt
	global_load_dwordx4 v[96:99], v[114:115], off offset:528 nt
	global_load_dwordx4 v[100:103], v[114:115], off offset:512 nt
	v_lshlrev_b64 v[136:137], 10, v[116:117]
	v_lshl_add_u64 v[136:137], v[136:137], 0, v[154:155]
	v_lshl_add_u64 v[136:137], v[136:137], 1, s[38:39]
	s_waitcnt vmcnt(7)
	v_pk_add_f32 v[94:95], v[94:95], v[120:121]
	v_pk_add_f32 v[92:93], v[92:93], v[118:119]
	s_waitcnt vmcnt(5)
	v_pk_add_f32 v[86:87], v[86:87], v[128:129]
	v_pk_add_f32 v[84:85], v[84:85], v[126:127]
	v_pk_add_f32 v[90:91], v[90:91], v[124:125]
	v_pk_add_f32 v[88:89], v[88:89], v[122:123]
	s_waitcnt vmcnt(4)
	v_pk_add_f32 v[80:81], v[80:81], v[130:131]
	global_store_dwordx4 v[134:135], v[92:95], off
	global_store_dwordx4 v[134:135], v[88:91], off offset:16
	v_cvt_pk_bf16_f32 v118, v92, v93
	v_cvt_pk_bf16_f32 v119, v94, v95
	v_mul_f32_e32 v122, v85, v85
	v_mul_f32_e32 v93, v93, v93
	v_mul_f32_e32 v95, v95, v95
	v_mul_f32_e32 v123, v87, v87
	v_pk_add_f32 v[82:83], v[82:83], v[132:133]
	v_cvt_pk_bf16_f32 v120, v88, v89
	v_mul_f32_e32 v89, v89, v89
	v_mul_f32_e32 v124, v81, v81
	v_fmac_f32_e32 v93, v92, v92
	v_fmac_f32_e32 v95, v94, v94
	v_fmac_f32_e32 v122, v84, v84
	v_fmac_f32_e32 v123, v86, v86
	v_cvt_pk_bf16_f32 v121, v90, v91
	v_mul_f32_e32 v91, v91, v91
	v_mul_f32_e32 v125, v83, v83
	global_store_dwordx4 v[136:137], v[118:121], off
	v_fmac_f32_e32 v89, v88, v88
	global_store_dwordx4 v[134:135], v[84:87], off offset:512
	global_store_dwordx4 v[134:135], v[80:83], off offset:528
	v_cvt_pk_bf16_f32 v88, v84, v85
	v_fmac_f32_e32 v124, v80, v80
	v_add_f32_e32 v84, v93, v95
	v_add_f32_e32 v85, v122, v123
	v_fmac_f32_e32 v91, v90, v90
	v_fmac_f32_e32 v125, v82, v82
	v_add_f32_e32 v84, v84, v89
	v_add_f32_e32 v85, v85, v124
	v_add_f32_e32 v84, v91, v84
	v_add_f32_e32 v85, v125, v85
	v_add_f32_e32 v84, v84, v85
	ds_swizzle_b32 v85, v84 offset:swizzle(SWAP,16)
	v_cvt_pk_bf16_f32 v89, v86, v87
	v_cvt_pk_bf16_f32 v90, v80, v81
	v_cvt_pk_bf16_f32 v91, v82, v83
	global_store_dwordx4 v[136:137], v[88:91], off offset:256
	s_waitcnt lgkmcnt(0)
	v_add_f32_e32 v80, v84, v85
	v_mov_b32_e32 v81, v80
	v_mov_b32_e32 v82, v80
	s_nop 1
	v_permlane32_swap_b32_e32 v81, v82
	s_and_saveexec_b64 s[0:1], vcc
	s_cbranch_execz .LBB0_939
	v_cmp_eq_u32_e64 s[42:43], v81, v80
	s_lshl_b32 s92, s57, 2
	s_nop 0
	v_cndmask_b32_e64 v81, v81, v82, s[42:43]
	v_add_f32_e32 v82, v80, v81
	v_lshlrev_b64 v[80:81], 6, v[116:117]
	v_lshl_add_u64 v[80:81], s[44:45], 0, v[80:81]
	v_lshl_add_u64 v[80:81], s[54:55], 2, v[80:81]
	v_lshl_add_u64 v[80:81], v[80:81], 0, s[92:93]
	global_store_dword v[80:81], v82, off

.LBB0_941:
	s_or_b64 exec, exec, s[0:1]
	v_add_u32_e32 v84, 0x80, v156
	v_ashrrev_i32_e32 v85, 31, v84
	v_lshlrev_b64 v[64:65], 12, v[84:85]
	v_lshl_add_u64 v[102:103], v[158:159], 0, v[64:65]
	global_load_dwordx4 v[86:89], v[102:103], off nt
	global_load_dwordx4 v[90:93], v[102:103], off offset:16 nt
	global_load_dwordx4 v[94:97], v[102:103], off offset:512 nt
	global_load_dwordx4 v[98:101], v[102:103], off offset:528 nt
	v_add_u32_e32 v80, 0x90, v156
	v_ashrrev_i32_e32 v81, 31, v80
	v_lshlrev_b64 v[64:65], 12, v[80:81]
	v_lshl_add_u64 v[82:83], v[158:159], 0, v[64:65]
	global_load_dwordx4 v[72:75], v[82:83], off offset:16 nt
	global_load_dwordx4 v[76:79], v[82:83], off nt
	global_load_dwordx4 v[64:67], v[82:83], off offset:528 nt
	global_load_dwordx4 v[68:71], v[82:83], off offset:512 nt
	v_lshlrev_b64 v[104:105], 10, v[84:85]
	v_lshl_add_u64 v[104:105], v[104:105], 0, v[154:155]
	v_lshl_add_u64 v[104:105], v[104:105], 1, s[38:39]
	s_waitcnt vmcnt(7)
	v_pk_add_f32 v[62:63], v[62:63], v[88:89]
	v_pk_add_f32 v[60:61], v[60:61], v[86:87]
	s_waitcnt vmcnt(5)
	v_pk_add_f32 v[54:55], v[54:55], v[96:97]
	v_pk_add_f32 v[52:53], v[52:53], v[94:95]
	v_pk_add_f32 v[58:59], v[58:59], v[92:93]
	v_pk_add_f32 v[56:57], v[56:57], v[90:91]
	s_waitcnt vmcnt(4)
	v_pk_add_f32 v[48:49], v[48:49], v[98:99]
	global_store_dwordx4 v[102:103], v[60:63], off
	global_store_dwordx4 v[102:103], v[56:59], off offset:16
	v_cvt_pk_bf16_f32 v86, v60, v61
	v_cvt_pk_bf16_f32 v87, v62, v63
	v_mul_f32_e32 v90, v53, v53
	v_mul_f32_e32 v61, v61, v61
	v_mul_f32_e32 v63, v63, v63
	v_mul_f32_e32 v91, v55, v55
	v_pk_add_f32 v[50:51], v[50:51], v[100:101]
	v_cvt_pk_bf16_f32 v88, v56, v57
	v_mul_f32_e32 v57, v57, v57
	v_mul_f32_e32 v92, v49, v49
	v_fmac_f32_e32 v61, v60, v60
	v_fmac_f32_e32 v63, v62, v62
	v_fmac_f32_e32 v90, v52, v52
	v_fmac_f32_e32 v91, v54, v54
	v_cvt_pk_bf16_f32 v89, v58, v59
	v_mul_f32_e32 v59, v59, v59
	v_mul_f32_e32 v93, v51, v51
	global_store_dwordx4 v[104:105], v[86:89], off
	v_fmac_f32_e32 v57, v56, v56
	global_store_dwordx4 v[102:103], v[52:55], off offset:512
	global_store_dwordx4 v[102:103], v[48:51], off offset:528
	v_cvt_pk_bf16_f32 v56, v52, v53
	v_fmac_f32_e32 v92, v48, v48
	v_add_f32_e32 v52, v61, v63
	v_add_f32_e32 v53, v90, v91
	v_fmac_f32_e32 v59, v58, v58
	v_fmac_f32_e32 v93, v50, v50
	v_add_f32_e32 v52, v52, v57
	v_add_f32_e32 v53, v53, v92
	v_add_f32_e32 v52, v59, v52
	v_add_f32_e32 v53, v93, v53
	v_add_f32_e32 v52, v52, v53
	ds_swizzle_b32 v53, v52 offset:swizzle(SWAP,16)
	v_cvt_pk_bf16_f32 v57, v54, v55
	v_cvt_pk_bf16_f32 v58, v48, v49
	v_cvt_pk_bf16_f32 v59, v50, v51
	global_store_dwordx4 v[104:105], v[56:59], off offset:256
	s_waitcnt lgkmcnt(0)
	v_add_f32_e32 v48, v52, v53
	v_mov_b32_e32 v49, v48
	v_mov_b32_e32 v50, v48
	s_nop 1
	v_permlane32_swap_b32_e32 v49, v50
	s_and_saveexec_b64 s[0:1], vcc
	s_cbranch_execz .LBB0_943
	v_cmp_eq_u32_e64 s[42:43], v49, v48
	s_lshl_b32 s92, s57, 2
	s_nop 0
	v_cndmask_b32_e64 v49, v49, v50, s[42:43]
	v_add_f32_e32 v50, v48, v49
	v_lshlrev_b64 v[48:49], 6, v[84:85]
	v_lshl_add_u64 v[48:49], s[44:45], 0, v[48:49]
	v_lshl_add_u64 v[48:49], s[54:55], 2, v[48:49]
	v_lshl_add_u64 v[48:49], v[48:49], 0, s[92:93]
	global_store_dword v[48:49], v50, off

.LBB0_945:
	s_or_b64 exec, exec, s[0:1]
	v_add_u32_e32 v52, 0xa0, v156
	v_ashrrev_i32_e32 v53, 31, v52
	v_lshlrev_b64 v[32:33], 12, v[52:53]
	v_lshl_add_u64 v[70:71], v[158:159], 0, v[32:33]
	global_load_dwordx4 v[54:57], v[70:71], off nt
	global_load_dwordx4 v[58:61], v[70:71], off offset:16 nt
	global_load_dwordx4 v[62:65], v[70:71], off offset:512 nt
	global_load_dwordx4 v[66:69], v[70:71], off offset:528 nt
	v_add_u32_e32 v48, 0xb0, v156
	v_ashrrev_i32_e32 v49, 31, v48
	v_lshlrev_b64 v[32:33], 12, v[48:49]
	v_lshl_add_u64 v[50:51], v[158:159], 0, v[32:33]
	global_load_dwordx4 v[40:43], v[50:51], off offset:16 nt
	global_load_dwordx4 v[44:47], v[50:51], off nt
	global_load_dwordx4 v[32:35], v[50:51], off offset:528 nt
	global_load_dwordx4 v[36:39], v[50:51], off offset:512 nt
	v_lshlrev_b64 v[72:73], 10, v[52:53]
	v_lshl_add_u64 v[72:73], v[72:73], 0, v[154:155]
	v_lshl_add_u64 v[72:73], v[72:73], 1, s[38:39]
	s_waitcnt vmcnt(7)
	v_pk_add_f32 v[30:31], v[30:31], v[56:57]
	v_pk_add_f32 v[28:29], v[28:29], v[54:55]
	s_waitcnt vmcnt(5)
	v_pk_add_f32 v[22:23], v[22:23], v[64:65]
	v_pk_add_f32 v[20:21], v[20:21], v[62:63]
	v_pk_add_f32 v[26:27], v[26:27], v[60:61]
	v_pk_add_f32 v[24:25], v[24:25], v[58:59]
	s_waitcnt vmcnt(4)
	v_pk_add_f32 v[16:17], v[16:17], v[66:67]
	global_store_dwordx4 v[70:71], v[28:31], off
	global_store_dwordx4 v[70:71], v[24:27], off offset:16
	v_cvt_pk_bf16_f32 v54, v28, v29
	v_cvt_pk_bf16_f32 v55, v30, v31
	v_mul_f32_e32 v58, v21, v21
	v_mul_f32_e32 v29, v29, v29
	v_mul_f32_e32 v31, v31, v31
	v_mul_f32_e32 v59, v23, v23
	v_pk_add_f32 v[18:19], v[18:19], v[68:69]
	v_cvt_pk_bf16_f32 v56, v24, v25
	v_mul_f32_e32 v25, v25, v25
	v_mul_f32_e32 v60, v17, v17
	v_fmac_f32_e32 v29, v28, v28
	v_fmac_f32_e32 v31, v30, v30
	v_fmac_f32_e32 v58, v20, v20
	v_fmac_f32_e32 v59, v22, v22
	v_cvt_pk_bf16_f32 v57, v26, v27
	v_mul_f32_e32 v27, v27, v27
	v_mul_f32_e32 v61, v19, v19
	global_store_dwordx4 v[72:73], v[54:57], off
	v_fmac_f32_e32 v25, v24, v24
	global_store_dwordx4 v[70:71], v[20:23], off offset:512
	global_store_dwordx4 v[70:71], v[16:19], off offset:528
	v_cvt_pk_bf16_f32 v24, v20, v21
	v_fmac_f32_e32 v60, v16, v16
	v_add_f32_e32 v20, v29, v31
	v_add_f32_e32 v21, v58, v59
	v_fmac_f32_e32 v27, v26, v26
	v_fmac_f32_e32 v61, v18, v18
	v_add_f32_e32 v20, v20, v25
	v_add_f32_e32 v21, v21, v60
	v_add_f32_e32 v20, v27, v20
	v_add_f32_e32 v21, v61, v21
	v_add_f32_e32 v20, v20, v21
	ds_swizzle_b32 v21, v20 offset:swizzle(SWAP,16)
	v_cvt_pk_bf16_f32 v25, v22, v23
	v_cvt_pk_bf16_f32 v26, v16, v17
	v_cvt_pk_bf16_f32 v27, v18, v19
	global_store_dwordx4 v[72:73], v[24:27], off offset:256
	s_waitcnt lgkmcnt(0)
	v_add_f32_e32 v16, v20, v21
	v_mov_b32_e32 v17, v16
	v_mov_b32_e32 v18, v16
	s_nop 1
	v_permlane32_swap_b32_e32 v17, v18
	s_and_saveexec_b64 s[0:1], vcc
	s_cbranch_execz .LBB0_947
	v_cmp_eq_u32_e64 s[42:43], v17, v16
	s_lshl_b32 s92, s57, 2
	s_nop 0
	v_cndmask_b32_e64 v17, v17, v18, s[42:43]
	v_add_f32_e32 v18, v16, v17
	v_lshlrev_b64 v[16:17], 6, v[52:53]
	v_lshl_add_u64 v[16:17], s[44:45], 0, v[16:17]
	v_lshl_add_u64 v[16:17], s[54:55], 2, v[16:17]
	v_lshl_add_u64 v[16:17], v[16:17], 0, s[92:93]
	global_store_dword v[16:17], v18, off

.LBB0_1007:
	global_load_dword v11, v[2:3], off
	global_load_dwordx4 v[12:15], v[4:5], off offset:-3072 nt
	global_load_dwordx4 v[16:19], v[0:1], off nt
	global_load_dwordx4 v[20:23], v[4:5], off offset:-2048 nt
	s_add_i32 s8, s8, s68
	v_lshl_add_u64 v[2:3], v[2:3], 0, s[0:1]
	s_cmpk_gt_i32 s8, 0x3fff
	s_waitcnt vmcnt(3)
	ds_bpermute_b32 v24, v6, v11
	s_waitcnt lgkmcnt(0)
	v_add_f32_e32 v11, v11, v24
	ds_bpermute_b32 v24, v7, v11
	s_waitcnt lgkmcnt(0)
	v_add_f32_e32 v11, v11, v24
	ds_bpermute_b32 v24, v8, v11
	s_waitcnt lgkmcnt(0)
	v_add_f32_e32 v11, v11, v24
	ds_bpermute_b32 v24, v9, v11
	s_waitcnt lgkmcnt(0)
	v_add_f32_e32 v11, v11, v24
	v_fmamk_f32 v11, v11, 0x3a800000, v10
	v_mul_f32_e32 v24, 0x4b800000, v11
	v_cmp_gt_f32_e32 vcc, s4, v11
	s_nop 1
	v_cndmask_b32_e32 v11, v11, v24, vcc
	v_rsq_f32_e32 v11, v11
	s_nop 0
	v_mul_f32_e32 v24, 0x45800000, v11
	v_cndmask_b32_e32 v24, v11, v24, vcc
	s_waitcnt vmcnt(2)
	v_pk_mul_f32 v[12:13], v[24:25], v[12:13] op_sel_hi:[0,1]
	v_pk_mul_f32 v[14:15], v[24:25], v[14:15] op_sel_hi:[0,1]
	s_waitcnt vmcnt(1)
	v_pk_mul_f32 v[14:15], v[14:15], v[18:19]
	v_pk_mul_f32 v[12:13], v[12:13], v[16:17]
	global_store_dwordx4 v[4:5], v[12:15], off offset:-3072
	global_load_dwordx4 v[12:15], v[0:1], off offset:1024 nt
	s_nop 0
	global_load_dwordx4 v[16:19], v[4:5], off offset:-1024 nt
	s_waitcnt vmcnt(3)
	v_pk_mul_f32 v[22:23], v[24:25], v[22:23] op_sel_hi:[0,1]
	v_pk_mul_f32 v[20:21], v[24:25], v[20:21] op_sel_hi:[0,1]
	s_waitcnt vmcnt(1)
	v_pk_mul_f32 v[12:13], v[20:21], v[12:13]
	v_pk_mul_f32 v[14:15], v[22:23], v[14:15]
	global_store_dwordx4 v[4:5], v[12:15], off offset:-2048
	global_load_dwordx4 v[12:15], v[0:1], off offset:2048 nt
	s_nop 0
	global_load_dwordx4 v[20:23], v[4:5], off nt
	s_waitcnt vmcnt(3)
	v_pk_mul_f32 v[18:19], v[24:25], v[18:19] op_sel_hi:[0,1]
	v_pk_mul_f32 v[16:17], v[24:25], v[16:17] op_sel_hi:[0,1]
	s_waitcnt vmcnt(1)
	v_pk_mul_f32 v[12:13], v[16:17], v[12:13]
	v_pk_mul_f32 v[14:15], v[18:19], v[14:15]
	global_store_dwordx4 v[4:5], v[12:15], off offset:-1024
	global_load_dwordx4 v[12:15], v[0:1], off offset:3072 nt
	s_waitcnt vmcnt(2)
	v_pk_mul_f32 v[16:17], v[24:25], v[22:23] op_sel_hi:[0,1]
	v_pk_mul_f32 v[18:19], v[24:25], v[20:21] op_sel_hi:[0,1]
	s_waitcnt vmcnt(0)
	v_pk_mul_f32 v[12:13], v[18:19], v[12:13]
	v_pk_mul_f32 v[14:15], v[16:17], v[14:15]
	global_store_dwordx4 v[4:5], v[12:15], off
	v_lshl_add_u64 v[4:5], v[4:5], 0, s[2:3]
	s_cbranch_scc0 .LBB0_1007
